# differential attention tile loop: back-edge rotation - LDS-DMA address formation moved in front of the pair barrier (7.11)
# baseline (speedup 1.0000x reference)
.LBB0_320:
	s_bitcmp1_b32 s26, 0
	s_cbranch_scc1 .Lda_tile
	s_cmp_ge_i32 s26, s34
	s_cbranch_scc1 .Lda_bar
	s_add_i32 s100, s26, 2
	v_readlane_b32 s98, v177, s100
	s_add_i32 s100, s26, 3
	s_add_i32 s101, s35, -1
	s_min_i32 s100, s100, s101
	s_lshl_b32 s98, s98, 17
	v_readlane_b32 s100, v177, s100
	v_lshl_add_u64 v[186:187], s[98:99], 0, v[178:179]
	v_lshl_add_u64 v[188:189], s[98:99], 0, v[180:181]
	s_lshl_b32 s100, s100, 17
	s_mov_b32 s101, 0
	v_lshl_add_u64 v[190:191], s[98:99], 0, v[182:183]
	v_lshl_add_u64 v[192:193], s[98:99], 0, v[184:185]
	v_lshl_add_u64 v[194:195], s[100:101], 0, v[178:179]
	v_lshl_add_u64 v[196:197], s[100:101], 0, v[180:181]
	v_lshl_add_u64 v[198:199], s[100:101], 0, v[182:183]
	v_lshl_add_u64 v[200:201], s[100:101], 0, v[184:185]
.Lda_bar:
	s_waitcnt vmcnt(0) lgkmcnt(0)
	s_barrier
.Lda_tile:
	v_readlane_b32 s3, v177, s26
	s_lshr_b32 s101, s95, 8
	s_xor_b32 s101, s101, s26
	s_bitcmp1_b32 s101, 0
	s_cbranch_scc1 .Lda_p1
	s_setprio 0
	s_branch .LBB0_319
